# v10 plus batched LDS reads in the P0 weight transpose loop and one static s_setprio 1 for waves 0-3 in the attention phase
# speedup vs baseline: 1.0006x; 1.0006x over previous
.LBB0_7:
	s_or_b64 exec, exec, s[10:11]
	ds_write2_b32 v81, v62, v63 offset1:1
	ds_write2_b32 v81, v64, v65 offset0:2 offset1:3
	v_add_u32_e32 v62, 0x420, v81
	ds_write2_b32 v62, v58, v59 offset1:1
	v_add_u32_e32 v58, 0x428, v81
	ds_write2_b32 v58, v60, v61 offset1:1
	v_add_u32_e32 v58, 0x840, v81
	ds_write2_b32 v58, v54, v55 offset1:1
	v_add_u32_e32 v54, 0x848, v81
	ds_write2_b32 v54, v56, v57 offset1:1
	v_add_u32_e32 v54, 0xc60, v81
	ds_write2_b32 v54, v50, v51 offset1:1
	v_add_u32_e32 v50, 0xc68, v81
	ds_write2_b32 v50, v52, v53 offset1:1
	v_add_u32_e32 v50, 0x1080, v81
	ds_write2_b32 v50, v38, v39 offset1:1
	v_add_u32_e32 v38, 0x1088, v81
	ds_write2_b32 v38, v40, v41 offset1:1
	v_add_u32_e32 v38, 0x14a0, v81
	ds_write2_b32 v38, v26, v27 offset1:1
	v_add_u32_e32 v26, 0x14a8, v81
	ds_write2_b32 v26, v28, v29 offset1:1
	v_add_u32_e32 v26, 0x18c0, v81
	ds_write2_b32 v26, v14, v15 offset1:1
	v_add_u32_e32 v14, 0x18c8, v81
	ds_write2_b32 v14, v16, v17 offset1:1
	v_add_u32_e32 v14, 0x1ce0, v81
	ds_write2_b32 v14, v10, v11 offset1:1
	v_add_u32_e32 v10, 0x1ce8, v81
	ds_write2_b32 v10, v12, v13 offset1:1
	s_waitcnt lgkmcnt(0)
	ds_read2_b32 v[100:101], v79 offset1:33
	ds_read2_b32 v[102:103], v79 offset0:66 offset1:99
	ds_read2_b32 v[104:105], v79 offset0:132 offset1:165
	ds_read2_b32 v[106:107], v79 offset0:198 offset1:231
	ds_read2_b32 v[108:109], v79 offset0:8 offset1:41
	ds_read2_b32 v[110:111], v79 offset0:74 offset1:107
	ds_read2_b32 v[112:113], v79 offset0:140 offset1:173
	ds_read2_b32 v[114:115], v79 offset0:206 offset1:239
	ds_read2_b32 v[116:117], v79 offset0:16 offset1:49
	ds_read2_b32 v[118:119], v79 offset0:82 offset1:115
	ds_read2_b32 v[120:121], v79 offset0:148 offset1:181
	ds_read2_b32 v[122:123], v79 offset0:214 offset1:247
	ds_read2_b32 v[124:125], v79 offset0:24 offset1:57
	ds_read2_b32 v[126:127], v79 offset0:90 offset1:123
	ds_read2_b32 v[128:129], v79 offset0:156 offset1:189
	ds_read2_b32 v[130:131], v79 offset0:222 offset1:255
	v_ashrrev_i32_e32 v14, 31, v83
	s_waitcnt lgkmcnt(15)
	v_cvt_pk_bf16_f32 v10, v100, v101
	v_add_u32_sdwa v14, v83, v14 dst_sel:DWORD dst_unused:UNUSED_PAD src0_sel:DWORD src1_sel:BYTE_3
	s_waitcnt lgkmcnt(14)
	v_cvt_pk_bf16_f32 v11, v102, v103
	v_ashrrev_i32_e32 v15, 8, v14
	s_waitcnt lgkmcnt(13)
	v_cvt_pk_bf16_f32 v12, v104, v105
	v_mul_i32_i24_e32 v13, 0x100, v15
	v_sub_u32_e32 v13, v83, v13
	v_lshlrev_b32_e32 v28, 5, v13
	s_waitcnt lgkmcnt(12)
	v_cvt_pk_bf16_f32 v13, v106, v107
	v_or_b32_e32 v16, v28, v75
	v_lshlrev_b32_e32 v14, 6, v15
	v_ashrrev_i32_e32 v17, 31, v16
	v_ashrrev_i32_e32 v15, 31, v14
	v_lshlrev_b64 v[16:17], 12, v[16:17]
	v_lshl_add_u64 v[16:17], s[70:71], 0, v[16:17]
	v_lshlrev_b64 v[14:15], 1, v[14:15]
	v_lshl_add_u64 v[16:17], v[16:17], 0, v[14:15]
	v_lshl_add_u64 v[16:17], v[16:17], 0, v[70:71]
	global_store_dwordx4 v[16:17], v[10:13], off sc0 sc1
	s_and_b64 s[4:5], exec, vcc
	s_waitcnt vmcnt(4)
	v_mov_b64_e32 v[40:41], v[36:37]
	s_waitcnt lgkmcnt(11)
	v_cvt_pk_bf16_f32 v10, v108, v109
	s_waitcnt lgkmcnt(10)
	v_cvt_pk_bf16_f32 v11, v110, v111
	s_waitcnt lgkmcnt(9)
	v_cvt_pk_bf16_f32 v12, v112, v113
	s_waitcnt lgkmcnt(8)
	v_cvt_pk_bf16_f32 v13, v114, v115
	v_or_b32_e32 v16, v28, v76
	v_ashrrev_i32_e32 v17, 31, v16
	v_lshlrev_b64 v[16:17], 12, v[16:17]
	v_lshl_add_u64 v[16:17], s[70:71], 0, v[16:17]
	v_lshl_add_u64 v[16:17], v[16:17], 0, v[14:15]
	v_lshl_add_u64 v[16:17], v[16:17], 0, v[70:71]
	global_store_dwordx4 v[16:17], v[10:13], off sc0 sc1
	v_mov_b64_e32 v[52:53], v[20:21]
	v_mov_b64_e32 v[56:57], v[24:25]
	s_waitcnt lgkmcnt(7)
	v_cvt_pk_bf16_f32 v10, v116, v117
	s_waitcnt lgkmcnt(6)
	v_cvt_pk_bf16_f32 v11, v118, v119
	s_waitcnt lgkmcnt(5)
	v_cvt_pk_bf16_f32 v12, v120, v121
	s_waitcnt lgkmcnt(4)
	v_cvt_pk_bf16_f32 v13, v122, v123
	v_or_b32_e32 v16, v28, v77
	v_ashrrev_i32_e32 v17, 31, v16
	v_lshlrev_b64 v[16:17], 12, v[16:17]
	v_lshl_add_u64 v[16:17], s[70:71], 0, v[16:17]
	v_lshl_add_u64 v[16:17], v[16:17], 0, v[14:15]
	v_lshl_add_u64 v[16:17], v[16:17], 0, v[70:71]
	global_store_dwordx4 v[16:17], v[10:13], off sc0 sc1
	v_mov_b64_e32 v[60:61], v[4:5]
	v_mov_b64_e32 v[64:65], v[8:9]
	s_waitcnt lgkmcnt(3)
	v_cvt_pk_bf16_f32 v10, v124, v125
	s_waitcnt lgkmcnt(2)
	v_cvt_pk_bf16_f32 v11, v126, v127
	s_waitcnt lgkmcnt(1)
	v_cvt_pk_bf16_f32 v12, v128, v129
	s_waitcnt lgkmcnt(0)
	v_cvt_pk_bf16_f32 v13, v130, v131
	v_or_b32_e32 v16, v28, v78
	v_ashrrev_i32_e32 v17, 31, v16
	v_lshlrev_b64 v[16:17], 12, v[16:17]
	v_lshl_add_u64 v[16:17], s[70:71], 0, v[16:17]
	v_lshl_add_u64 v[14:15], v[16:17], 0, v[14:15]
	v_lshl_add_u64 v[14:15], v[14:15], 0, v[70:71]
	global_store_dwordx4 v[14:15], v[10:13], off sc0 sc1
	s_waitcnt lgkmcnt(0)
	s_waitcnt vmcnt(5)
	v_mov_b64_e32 v[14:15], v[46:47]
	v_mov_b64_e32 v[26:27], v[30:31]
	s_waitcnt vmcnt(4)
	v_mov_b64_e32 v[10:11], v[42:43]
	s_or_b64 s[6:7], s[4:5], s[6:7]
	v_add_u32_e32 v80, s13, v80
	v_mov_b64_e32 v[12:13], v[44:45]
	v_mov_b64_e32 v[16:17], v[48:49]
	v_mov_b64_e32 v[28:29], v[32:33]
	v_mov_b64_e32 v[38:39], v[34:35]
	v_mov_b64_e32 v[50:51], v[18:19]
	v_mov_b64_e32 v[54:55], v[22:23]
	v_mov_b64_e32 v[58:59], v[2:3]
	v_mov_b64_e32 v[62:63], v[6:7]
	v_mov_b32_e32 v83, v73
	s_andn2_b64 exec, exec, s[6:7]
	s_cbranch_execz .LBB0_10
